# v13 (attention PV ladder + over-drain fix) + P2 row loop counted vmcnt instead of per-row store drain
# baseline (speedup 1.0000x reference)
.LBB0_286:
	v_readlane_b32 s0, v253, 3
	v_readlane_b32 s1, v254, 28
	v_lshlrev_b32_e32 v44, 3, v128
	s_add_i32 s49, s1, s0
	v_and_b32_e32 v62, 8, v44
	s_cmpk_lt_i32 s49, 0x4000
	v_and_b32_e32 v45, 15, v130
	v_cmp_gt_u32_e64 s[6:7], 32, v128
	v_cmp_lt_u32_e64 s[0:1], 31, v128
	s_mov_b64 s[16:17], s[94:95]
	s_cbranch_scc0 .LBB0_314
	s_waitcnt vmcnt(0)
	v_and_b32_e32 v16, 24, v44
	v_cvt_f32_ubyte0_e32 v0, v16
	v_mul_f32_e32 v1, 0xbed49a78, v0
	s_mov_b32 s9, 0xc2fc0000
	v_cmp_gt_f32_e32 vcc, s9, v1
	s_lshl_b32 s8, s82, 8
	s_mul_i32 s5, s49, 0x2a00
	v_cndmask_b32_e32 v1, 0, v217, vcc
	v_fmac_f32_e32 v1, 0xbed49a78, v0
	v_exp_f32_e32 v0, v1
	v_cvt_f32_ubyte0_e32 v1, v62
	v_mul_f32_e32 v2, 0xbf549a78, v1
	v_cmp_gt_f32_e64 s[2:3], s9, v2
	s_mul_hi_i32 s4, s49, 0x2a00
	v_lshlrev_b32_e32 v8, 1, v44
	v_cndmask_b32_e64 v3, 0, v217, s[2:3]
	v_fmac_f32_e32 v3, 0xbf549a78, v1
	v_exp_f32_e32 v1, v3
	v_cndmask_b32_e32 v3, 0, v218, vcc
	v_ldexp_f32 v63, v0, v3
	v_or_b32_e32 v0, 1, v16
	v_cndmask_b32_e64 v2, 0, v218, s[2:3]
	v_cvt_f32_ubyte0_e32 v0, v0
	v_ldexp_f32 v64, v1, v2
	v_mul_f32_e32 v1, 0xbed49a78, v0
	v_cmp_gt_f32_e32 vcc, s9, v1
	v_mov_b32_e32 v9, v179
	v_add_u32_e32 v178, 0xffffff00, v44
	v_cndmask_b32_e32 v1, 0, v217, vcc
	v_fmac_f32_e32 v1, 0xbed49a78, v0
	v_exp_f32_e32 v0, v1
	v_or_b32_e32 v1, 1, v62
	v_cvt_f32_ubyte0_e32 v1, v1
	v_mul_f32_e32 v2, 0xbf549a78, v1
	v_cmp_gt_f32_e64 s[2:3], s9, v2
	s_mov_b64 s[10:11], 0xa000000
	s_mov_b32 s34, s49
	v_cndmask_b32_e64 v2, 0, v217, s[2:3]
	v_fmac_f32_e32 v2, 0xbf549a78, v1
	v_exp_f32_e32 v1, v2
	v_cndmask_b32_e32 v2, 0, v218, vcc
	v_ldexp_f32 v65, v0, v2
	v_cndmask_b32_e64 v0, 0, v218, s[2:3]
	v_ldexp_f32 v66, v1, v0
	v_or_b32_e32 v0, 2, v16
	v_cvt_f32_ubyte0_e32 v0, v0
	v_mul_f32_e32 v1, 0xbed49a78, v0
	v_cmp_gt_f32_e32 vcc, s9, v1
	s_load_dwordx4 s[12:15], s[16:17], 0xb8
	s_nop 0
	v_cndmask_b32_e32 v1, 0, v217, vcc
	v_fmac_f32_e32 v1, 0xbed49a78, v0
	v_exp_f32_e32 v0, v1
	v_or_b32_e32 v1, 2, v62
	v_cvt_f32_ubyte0_e32 v1, v1
	v_mul_f32_e32 v2, 0xbf549a78, v1
	v_cmp_gt_f32_e64 s[2:3], s9, v2
	s_nop 1
	v_cndmask_b32_e64 v2, 0, v217, s[2:3]
	v_fmac_f32_e32 v2, 0xbf549a78, v1
	v_exp_f32_e32 v1, v2
	v_cndmask_b32_e32 v2, 0, v218, vcc
	v_ldexp_f32 v67, v0, v2
	v_cndmask_b32_e64 v0, 0, v218, s[2:3]
	v_ldexp_f32 v68, v1, v0
	v_or_b32_e32 v0, 3, v16
	v_cvt_f32_ubyte0_e32 v0, v0
	v_mul_f32_e32 v1, 0xbed49a78, v0
	v_cmp_gt_f32_e32 vcc, s9, v1
	s_nop 1
	v_cndmask_b32_e32 v1, 0, v217, vcc
	v_fmac_f32_e32 v1, 0xbed49a78, v0
	v_exp_f32_e32 v0, v1
	v_or_b32_e32 v1, 3, v62
	v_cvt_f32_ubyte0_e32 v1, v1
	v_mul_f32_e32 v2, 0xbf549a78, v1
	v_cmp_gt_f32_e64 s[2:3], s9, v2
	s_nop 1
	v_cndmask_b32_e64 v2, 0, v217, s[2:3]
	v_fmac_f32_e32 v2, 0xbf549a78, v1
	v_exp_f32_e32 v1, v2
	v_cndmask_b32_e32 v2, 0, v218, vcc
	v_ldexp_f32 v69, v0, v2
	v_cndmask_b32_e64 v0, 0, v218, s[2:3]
	v_ldexp_f32 v70, v1, v0
	v_or_b32_e32 v0, 4, v16
	v_cvt_f32_ubyte0_e32 v0, v0
	v_mul_f32_e32 v1, 0xbed49a78, v0
	v_cmp_gt_f32_e32 vcc, s9, v1
	s_nop 1
	v_cndmask_b32_e32 v1, 0, v217, vcc
	v_fmac_f32_e32 v1, 0xbed49a78, v0
	v_exp_f32_e32 v0, v1
	v_or_b32_e32 v1, 4, v62
	v_cvt_f32_ubyte0_e32 v1, v1
	v_mul_f32_e32 v2, 0xbf549a78, v1
	v_cmp_gt_f32_e64 s[2:3], s9, v2
	s_nop 1
	v_cndmask_b32_e64 v2, 0, v217, s[2:3]
	v_fmac_f32_e32 v2, 0xbf549a78, v1
	v_exp_f32_e32 v1, v2
	v_cndmask_b32_e32 v2, 0, v218, vcc
	v_ldexp_f32 v71, v0, v2
	v_cndmask_b32_e64 v0, 0, v218, s[2:3]
	v_ldexp_f32 v72, v1, v0
	v_or_b32_e32 v0, 5, v16
	v_cvt_f32_ubyte0_e32 v0, v0
	v_mul_f32_e32 v1, 0xbed49a78, v0
	v_cmp_gt_f32_e32 vcc, s9, v1
	s_nop 1
	v_cndmask_b32_e32 v1, 0, v217, vcc
	v_fmac_f32_e32 v1, 0xbed49a78, v0
	v_exp_f32_e32 v0, v1
	v_or_b32_e32 v1, 5, v62
	v_cvt_f32_ubyte0_e32 v1, v1
	v_mul_f32_e32 v2, 0xbf549a78, v1
	v_cmp_gt_f32_e64 s[2:3], s9, v2
	s_nop 1
	v_cndmask_b32_e64 v2, 0, v217, s[2:3]
	v_fmac_f32_e32 v2, 0xbf549a78, v1
	v_exp_f32_e32 v1, v2
	v_cndmask_b32_e32 v2, 0, v218, vcc
	v_ldexp_f32 v73, v0, v2
	v_cndmask_b32_e64 v0, 0, v218, s[2:3]
	s_load_dwordx2 s[2:3], s[16:17], 0x80
	v_ldexp_f32 v74, v1, v0
	v_or_b32_e32 v0, 6, v16
	v_cvt_f32_ubyte0_e32 v17, v0
	v_lshl_or_b32 v0, v45, 3, s8
	v_mov_b32_e32 v1, v179
	s_waitcnt lgkmcnt(0)
	v_lshl_add_u64 v[4:5], v[0:1], 2, s[2:3]
	s_add_u32 s2, s14, s5
	s_addc_u32 s3, s15, s4
	v_lshl_add_u64 v[8:9], s[2:3], 0, v[8:9]
	s_mov_b32 s2, 0x1b800000
	v_add_co_u32_e32 v10, vcc, s2, v8
	s_mov_b32 s2, 0x1b802000
	s_nop 0
	v_addc_co_u32_e32 v11, vcc, 0, v9, vcc
	v_add_co_u32_e32 v8, vcc, s2, v8
	global_load_dwordx4 v[0:3], v[4:5], off offset:528
	s_nop 0
	global_load_dwordx4 v[4:7], v[4:5], off offset:512
	v_addc_co_u32_e32 v9, vcc, 0, v9, vcc
	global_load_dwordx4 v[28:31], v[10:11], off offset:2048
	global_load_dwordx4 v[12:15], v[8:9], off
	s_nop 0
	global_load_dwordx4 v[8:11], v[8:9], off offset:1024
	v_mul_f32_e32 v18, 0xbed49a78, v17
	v_cmp_gt_f32_e32 vcc, s9, v18
	v_or_b32_e32 v16, 7, v16
	v_cvt_f32_ubyte0_e32 v16, v16
	v_cndmask_b32_e32 v18, 0, v217, vcc
	v_fmac_f32_e32 v18, 0xbed49a78, v17
	v_exp_f32_e32 v17, v18
	v_or_b32_e32 v18, 6, v62
	v_cvt_f32_ubyte0_e32 v18, v18
	v_mul_f32_e32 v19, 0xbf549a78, v18
	v_cmp_gt_f32_e64 s[2:3], s9, v19
	s_add_u32 s28, s14, 0x26000000
	s_addc_u32 s29, s15, 0
	v_cndmask_b32_e64 v19, 0, v217, s[2:3]
	v_fmac_f32_e32 v19, 0xbf549a78, v18
	v_exp_f32_e32 v18, v19
	v_cndmask_b32_e32 v19, 0, v218, vcc
	v_ldexp_f32 v75, v17, v19
	v_cndmask_b32_e64 v17, 0, v218, s[2:3]
	v_ldexp_f32 v76, v18, v17
	v_mul_f32_e32 v17, 0xbed49a78, v16
	v_cmp_gt_f32_e32 vcc, s9, v17
	s_add_u32 s30, s14, 0x27900000
	s_addc_u32 s31, s15, 0
	v_cndmask_b32_e32 v17, 0, v217, vcc
	v_fmac_f32_e32 v17, 0xbed49a78, v16
	v_exp_f32_e32 v16, v17
	v_or_b32_e32 v17, 7, v62
	v_cvt_f32_ubyte0_e32 v17, v17
	v_mul_f32_e32 v18, 0xbf549a78, v17
	v_cmp_gt_f32_e64 s[2:3], s9, v18
	v_cmp_gt_u32_e64 s[8:9], 8, v45
	s_nop 0
	v_cndmask_b32_e64 v18, 0, v217, s[2:3]
	v_fmac_f32_e32 v18, 0xbf549a78, v17
	v_exp_f32_e32 v17, v18
	v_cndmask_b32_e32 v18, 0, v218, vcc
	v_ldexp_f32 v77, v16, v18
	v_cndmask_b32_e64 v16, 0, v218, s[2:3]
	v_ldexp_f32 v78, v17, v16
	v_and_b32_e32 v16, 4, v130
	v_cmp_eq_u32_e64 s[2:3], 0, v16
	v_and_b32_e32 v16, 2, v130
	v_and_b32_e32 v17, 64, v219
	v_cmp_eq_u32_e64 s[4:5], 0, v16
	v_xor_b32_e32 v16, 1, v219
	v_add_u32_e32 v17, 64, v17
	v_cmp_lt_i32_e32 vcc, v16, v17
	s_nop 1
	v_cndmask_b32_e32 v16, v219, v16, vcc
	v_lshlrev_b32_e32 v79, 2, v16
	v_xor_b32_e32 v16, 2, v219
	v_cmp_lt_i32_e32 vcc, v16, v17
	s_nop 1
	v_cndmask_b32_e32 v16, v219, v16, vcc
	v_lshlrev_b32_e32 v80, 2, v16
	v_xor_b32_e32 v16, 4, v219
	v_cmp_lt_i32_e32 vcc, v16, v17
	s_nop 1
	v_cndmask_b32_e32 v16, v219, v16, vcc
	v_lshlrev_b32_e32 v81, 2, v16
	v_xor_b32_e32 v16, 8, v219
	v_cmp_lt_i32_e32 vcc, v16, v17
	s_nop 1
	v_cndmask_b32_e32 v16, v219, v16, vcc
	v_lshlrev_b32_e32 v82, 2, v16
	v_lshl_add_u64 v[16:17], v[178:179], 2, s[12:13]
	v_lshl_add_u64 v[46:47], v[16:17], 0, s[10:11]
	v_lshlrev_b32_e32 v16, 2, v44
	v_mov_b32_e32 v17, v179
	v_lshl_add_u64 v[16:17], s[12:13], 0, v[16:17]
	s_mov_b64 s[10:11], 0x8000000
	v_lshl_add_u64 v[48:49], v[16:17], 0, s[10:11]
	s_mov_b64 s[10:11], 0xc000000
	v_lshl_add_u64 v[50:51], v[16:17], 0, s[10:11]
	s_mov_b64 s[10:11], 0x10000000
	v_lshl_add_u64 v[52:53], v[16:17], 0, s[10:11]
	v_readlane_b32 s10, v253, 39
	v_readlane_b32 s11, v254, 28
	s_add_i32 s10, s10, s11
	s_mul_hi_i32 s11, s10, 0x2a00
	s_mulk_i32 s10, 0x2a00
	v_and_b32_e32 v16, 63, v130
	s_add_u32 s10, s14, s10
	v_lshlrev_b32_e32 v16, 4, v16
	v_mov_b32_e32 v17, v179
	s_addc_u32 s11, s15, s11
	v_lshl_add_u64 v[16:17], s[10:11], 0, v[16:17]
	s_mov_b64 s[10:11], 0x1b800800
	v_lshl_add_u64 v[54:55], v[16:17], 0, s[10:11]
	s_waitcnt vmcnt(0)
	s_branch .LBB0_289
.LBB0_288:
	v_readlane_b32 s10, v253, 40
	v_readlane_b32 s11, v253, 41
	s_waitcnt vmcnt(6)
	v_mov_b64_e32 v[30:31], v[18:19]
	s_waitcnt vmcnt(5)
	v_mov_b64_e32 v[12:13], v[24:25]
	s_waitcnt vmcnt(4)
	v_mov_b64_e32 v[8:9], v[20:21]
	v_lshl_add_u64 v[54:55], v[54:55], 0, s[10:11]
	s_and_b64 vcc, exec, s[12:13]
	v_mov_b64_e32 v[28:29], v[16:17]
	v_mov_b64_e32 v[14:15], v[26:27]
	v_mov_b64_e32 v[10:11], v[22:23]
	s_cbranch_vccnz .LBB0_314

.LBB0_294:
	s_add_i32 s34, s34, s97
	s_cmpk_gt_i32 s34, 0x3fff
	s_cselect_b64 s[12:13], -1, 0
	v_mov_b64_e32 v[22:23], v[10:11]
	v_mov_b64_e32 v[26:27], v[14:15]
	v_mov_b64_e32 v[16:17], v[28:29]
	s_and_b64 vcc, exec, s[12:13]
	v_mov_b64_e32 v[20:21], v[8:9]
	v_mov_b64_e32 v[24:25], v[12:13]
	v_mov_b64_e32 v[18:19], v[30:31]
	s_cbranch_vccnz .LBB0_296
	v_add_co_u32_e32 v20, vcc, 0x1000, v54
	global_load_dwordx4 v[16:19], v[54:55], off
	s_nop 0
	v_addc_co_u32_e32 v21, vcc, 0, v55, vcc
	global_load_dwordx4 v[24:27], v[20:21], off offset:2048
	s_nop 0
	global_load_dwordx4 v[20:23], v[20:21], off offset:3072
